# grid barrier: XCD leader publishes the per-XCD generation before its own acquire invalidate
# speedup vs baseline: 1.0554x; 1.0002x over previous
; __device__ __forceinline__ unsigned xb_add(unsigned* p, unsigned v) { return __hip_atomic_fetch_add(p, v, __ATOMIC_RELAXED, __HIP_MEMORY_SCOPE_AGENT); }
; __device__ __forceinline__ void xcd_barrier(const XcdBarrier& b) {
;     ...
;             __builtin_amdgcn_fence(__ATOMIC_ACQUIRE, "agent");
;             xb_add(&bar[XB_XGEN(b.x)], 1u);
;             asm volatile("s_waitcnt vmcnt(0)" ::: "memory");
.LBB0_349:
	s_or_b64 exec, exec, s[20:21]
	buffer_inv sc1
	s_waitcnt vmcnt(0)

; __device__ __forceinline__ unsigned xb_add(unsigned* p, unsigned v) { return __hip_atomic_fetch_add(p, v, __ATOMIC_RELAXED, __HIP_MEMORY_SCOPE_AGENT); }
; __device__ __forceinline__ void xcd_barrier(const XcdBarrier& b) {
;     ...
;             __builtin_amdgcn_fence(__ATOMIC_ACQUIRE, "agent");
;             xb_add(&bar[XB_XGEN(b.x)], 1u);
.LBB0_415:
	s_or_b64 exec, exec, s[6:7]
	s_mov_b64 s[6:7], exec
	v_mbcnt_lo_u32_b32 v0, s6, 0
	v_mbcnt_hi_u32_b32 v0, s7, v0
	v_cmp_eq_u32_e32 vcc, 0, v0
	s_waitcnt vmcnt(0)
	s_and_saveexec_b64 s[20:21], vcc
	s_cbranch_execz .LBB0_417
	s_bcnt1_i32_b64 s6, s[6:7]
	v_mov_b32_e32 v0, s6
	v_readlane_b32 s6, v254, 7
	v_readlane_b32 s7, v254, 8
	s_nop 4
	global_atomic_add v1, v0, s[6:7]

; __device__ __forceinline__ unsigned xb_add(unsigned* p, unsigned v) { return __hip_atomic_fetch_add(p, v, __ATOMIC_RELAXED, __HIP_MEMORY_SCOPE_AGENT); }
; __device__ __forceinline__ void xcd_barrier(const XcdBarrier& b) {
;     ...
;             __builtin_amdgcn_fence(__ATOMIC_ACQUIRE, "agent");
;             xb_add(&bar[XB_XGEN(b.x)], 1u);
.LBB0_1501:
	s_or_b64 exec, exec, s[6:7]
	s_mov_b64 s[6:7], exec
	v_mbcnt_lo_u32_b32 v0, s6, 0
	v_mbcnt_hi_u32_b32 v0, s7, v0
	v_cmp_eq_u32_e32 vcc, 0, v0
	s_waitcnt vmcnt(0)
	s_and_saveexec_b64 s[20:21], vcc
	s_cbranch_execnz .LBB0_1502
	s_getpc_b64 s[98:99]
